# GDN scan: next-chunk image loads issued between the first 8 MFMAs of the chunk instead of back-to-back at the chunk top; z wait moved in front of them
# speedup vs baseline: 1.0124x; 1.0032x over previous
.LBB0_709:
	ds_read_b128 v[128:131], v161 offset:18432
	ds_read_b128 v[174:177], v161 offset:18496
	ds_read_b128 v[178:181], v161 offset:23040
	ds_read_b128 v[182:185], v161 offset:23104
	ds_read_b128 v[186:189], v161 offset:27648
	ds_read_b128 v[190:193], v161 offset:27712
	ds_read_b128 v[194:197], v161 offset:32256
	ds_read_b128 v[202:205], v161 offset:32320
	ds_read_b128 v[206:209], v161 offset:18560
	ds_read_b128 v[210:213], v161 offset:18624
	ds_read_b128 v[214:217], v161 offset:23168
	ds_read_b128 v[218:221], v161 offset:23232
	ds_read_b128 v[222:225], v161 offset:27776
	ds_read_b128 v[226:229], v161 offset:27840
	ds_read_b128 v[230:233], v161 offset:32384
	ds_read_b128 v[234:237], v161 offset:32448
	ds_read_u16 v238, v170 offset:36864
	ds_read_u16 v239, v170 offset:37152
	ds_read_u16 v240, v170 offset:37440
	ds_read_u16 v241, v170 offset:37728
	ds_read_u16 v242, v170 offset:41472
	ds_read_u16 v243, v170 offset:41760
	ds_read_u16 v244, v170 offset:42048
	ds_read_u16 v245, v170 offset:42336
	ds_read_u16 v246, v170 offset:46080
	ds_read_u16 v247, v170 offset:46368
	ds_read_u16 v248, v170 offset:46656
	ds_read_u16 v249, v170 offset:46944
	ds_read_u16 v250, v170 offset:50688
	ds_read_u16 v251, v170 offset:50976
	ds_read_u16 v252, v170 offset:51264
	ds_read_u16 v253, v170 offset:51552
	s_cmp_lg_u32 s0, 1
	s_cselect_b64 s[8:9], -1, 0
	s_cmp_eq_u32 s0, 1
	s_cbranch_scc1 .LBB0_711
	v_lshl_add_u64 v[36:37], s[92:93], 0, v[122:123]
	v_lshl_add_u64 v[16:17], s[92:93], 0, v[124:125]
	v_add_co_u32_e32 v4, vcc, 0x1a004000, v16
	v_lshl_add_u64 v[24:25], s[92:93], 0, v[126:127]
	s_nop 0
	v_addc_co_u32_e32 v5, vcc, 0, v17, vcc
	v_add_co_u32_e32 v12, vcc, 0x1c004000, v16
	s_add_u32 s10, s92, s17
	s_nop 0
	v_addc_co_u32_e32 v13, vcc, 0, v17, vcc
	v_add_co_u32_e32 v20, vcc, 0x1e004000, v16
	s_addc_u32 s11, s93, s18
	s_nop 0
	v_addc_co_u32_e32 v21, vcc, 0, v17, vcc
	v_add_co_u32_e32 v28, vcc, 0x2058000, v24
	s_nop 1
	v_addc_co_u32_e32 v29, vcc, 0, v25, vcc
	v_add_co_u32_e32 v36, vcc, 0x2058000, v36
	s_nop 1
	v_addc_co_u32_e32 v37, vcc, 0, v37, vcc
.LBB0_711:
	v_cvt_pk_bf16_f32 v92, v52, v53
	v_cvt_pk_bf16_f32 v93, v54, v55
	v_cvt_pk_bf16_f32 v94, v48, v49
	v_cvt_pk_bf16_f32 v95, v50, v51
	v_cvt_pk_bf16_f32 v88, v44, v45
	v_cvt_pk_bf16_f32 v89, v46, v47
	v_cvt_pk_bf16_f32 v90, v40, v41
	v_cvt_pk_bf16_f32 v91, v42, v43
	v_cvt_pk_bf16_f32 v84, v60, v61
	v_cvt_pk_bf16_f32 v85, v62, v63
	v_cvt_pk_bf16_f32 v86, v56, v57
	v_cvt_pk_bf16_f32 v87, v58, v59
	v_cvt_pk_bf16_f32 v80, v64, v65
	v_cvt_pk_bf16_f32 v81, v66, v67
	v_cvt_pk_bf16_f32 v82, v68, v69
	v_cvt_pk_bf16_f32 v83, v70, v71
	s_waitcnt lgkmcnt(0)
	v_lshlrev_b32_e32 v238, 16, v238
	v_lshlrev_b32_e32 v239, 16, v239
	v_lshlrev_b32_e32 v240, 16, v240
	v_lshlrev_b32_e32 v241, 16, v241
	v_lshlrev_b32_e32 v242, 16, v242
	v_lshlrev_b32_e32 v243, 16, v243
	v_lshlrev_b32_e32 v244, 16, v244
	v_lshlrev_b32_e32 v245, 16, v245
	v_lshlrev_b32_e32 v246, 16, v246
	v_lshlrev_b32_e32 v247, 16, v247
	v_lshlrev_b32_e32 v248, 16, v248
	v_lshlrev_b32_e32 v249, 16, v249
	v_lshlrev_b32_e32 v250, 16, v250
	v_lshlrev_b32_e32 v251, 16, v251
	v_lshlrev_b32_e32 v252, 16, v252
	v_lshlrev_b32_e32 v253, 16, v253
	s_waitcnt vmcnt(2)
	s_cmp_lg_u64 s[8:9], 0
	s_cbranch_scc0 .Lscan_b1_plain
	v_mfma_f32_16x16x32_bf16 v[128:131], v[128:131], v[92:95], v[238:241]
	global_load_dwordx4 v[0:3], v[4:5], off
	v_mfma_f32_16x16x32_bf16 v[178:181], v[178:181], v[92:95], v[242:245]
	global_load_dwordx4 v[4:7], v[4:5], off offset:16
	v_mfma_f32_16x16x32_bf16 v[186:189], v[186:189], v[92:95], v[246:249]
	global_load_dwordx4 v[8:11], v[12:13], off
	v_mfma_f32_16x16x32_bf16 v[194:197], v[194:197], v[92:95], v[250:253]
	global_load_dwordx4 v[12:15], v[12:13], off offset:16
	v_mfma_f32_16x16x32_bf16 v[128:131], v[174:177], v[88:91], v[128:131]
	global_load_dwordx4 v[16:19], v[20:21], off
	v_mfma_f32_16x16x32_bf16 v[174:177], v[182:185], v[88:91], v[178:181]
	global_load_dwordx4 v[20:23], v[20:21], off offset:16
	s_nop 0
	global_load_dwordx4 v[24:27], v[28:29], off offset:1152
	v_mfma_f32_16x16x32_bf16 v[178:181], v[190:193], v[88:91], v[186:189]
	global_load_dwordx4 v[28:31], v[28:29], off offset:1280
	s_nop 0
	global_load_dwordx4 v[32:35], v[36:37], off offset:2176
	v_mfma_f32_16x16x32_bf16 v[182:185], v[202:205], v[88:91], v[194:197]
	global_load_dwordx4 v[36:39], v[36:37], off offset:2192
	s_nop 0
	global_load_dword v172, v103, s[10:11]
	s_branch .Lscan_b1_join
.Lscan_b1_plain:
	v_mfma_f32_16x16x32_bf16 v[128:131], v[128:131], v[92:95], v[238:241]
	v_mfma_f32_16x16x32_bf16 v[178:181], v[178:181], v[92:95], v[242:245]
	v_mfma_f32_16x16x32_bf16 v[186:189], v[186:189], v[92:95], v[246:249]
	v_mfma_f32_16x16x32_bf16 v[194:197], v[194:197], v[92:95], v[250:253]
	v_mfma_f32_16x16x32_bf16 v[128:131], v[174:177], v[88:91], v[128:131]
	v_mfma_f32_16x16x32_bf16 v[174:177], v[182:185], v[88:91], v[178:181]
	v_mfma_f32_16x16x32_bf16 v[178:181], v[190:193], v[88:91], v[186:189]
	v_mfma_f32_16x16x32_bf16 v[182:185], v[202:205], v[88:91], v[194:197]
.Lscan_b1_join:
	s_nop 2
	ds_read_b128 v[186:189], v161
	ds_read_b128 v[190:193], v161 offset:64
	ds_read_b128 v[194:197], v161 offset:4608
	ds_read_b128 v[202:205], v161 offset:4672
	ds_read_b128 v[238:241], v161 offset:9216
	ds_read_b128 v[242:245], v161 offset:9280
	ds_read_b128 v[246:249], v161 offset:13824
	ds_read_b128 v[250:253], v161 offset:13888
	v_mfma_f32_16x16x32_bf16 v[128:131], v[206:209], v[84:87], v[128:131]
	v_lshlrev_b32_e32 v96, 16, v76
	v_and_b32_e32 v97, 0xffff0000, v76
	v_mul_f32_e32 v76, 0xbfb8aa3b, v96
	v_mfma_f32_16x16x32_bf16 v[174:177], v[214:217], v[84:87], v[174:177]
	v_mul_f32_e32 v102, 0xbfb8aa3b, v97
	v_exp_f32_e32 v76, v76
	v_exp_f32_e32 v102, v102
	v_mfma_f32_16x16x32_bf16 v[178:181], v[222:225], v[84:87], v[178:181]
	v_add_f32_e32 v76, 1.0, v76
	v_add_f32_e32 v102, 1.0, v102
	v_rcp_f32_e32 v76, v76
	v_mfma_f32_16x16x32_bf16 v[182:185], v[230:233], v[84:87], v[182:185]
	v_rcp_f32_e32 v102, v102
	v_mul_f32_e32 v96, v76, v96
	v_mul_f32_e32 v97, v102, v97
	v_mfma_f32_16x16x32_bf16 v[128:131], v[210:213], v[80:83], v[128:131]
	v_lshlrev_b32_e32 v98, 16, v77
	v_and_b32_e32 v99, 0xffff0000, v77
	v_mul_f32_e32 v77, 0xbfb8aa3b, v98
	v_mfma_f32_16x16x32_bf16 v[174:177], v[218:221], v[80:83], v[174:177]
	v_mul_f32_e32 v102, 0xbfb8aa3b, v99
	v_exp_f32_e32 v77, v77
	v_exp_f32_e32 v102, v102
	v_mfma_f32_16x16x32_bf16 v[178:181], v[226:229], v[80:83], v[178:181]
	v_add_f32_e32 v77, 1.0, v77
	v_add_f32_e32 v102, 1.0, v102
	v_rcp_f32_e32 v77, v77
	v_mfma_f32_16x16x32_bf16 v[182:185], v[234:237], v[80:83], v[182:185]
	v_rcp_f32_e32 v102, v102
	v_mul_f32_e32 v98, v77, v98
	v_mul_f32_e32 v99, v102, v99
	ds_read_b128 v[206:209], v161 offset:128
	ds_read_b128 v[210:213], v161 offset:192
	ds_read_b128 v[214:217], v161 offset:4736
	ds_read_b128 v[218:221], v161 offset:4800
	ds_read_b128 v[222:225], v161 offset:9344
	ds_read_b128 v[226:229], v161 offset:9408
	ds_read_b128 v[230:233], v161 offset:13952
	ds_read_b128 v[234:237], v161 offset:14016
	v_cvt_pk_bf16_f32 v128, v128, v129
	v_cvt_pk_bf16_f32 v129, v130, v131
	v_cvt_pk_bf16_f32 v130, v174, v175
	v_cvt_pk_bf16_f32 v131, v176, v177
	v_cvt_pk_bf16_f32 v174, v178, v179
	v_cvt_pk_bf16_f32 v175, v180, v181
	v_cvt_pk_bf16_f32 v176, v182, v183
	v_cvt_pk_bf16_f32 v177, v184, v185
	s_waitcnt lgkmcnt(14)
	v_mfma_f32_16x16x32_bf16 v[178:181], v[186:189], v[92:95], 0
	v_lshlrev_b32_e32 v100, 16, v78
	v_and_b32_e32 v101, 0xffff0000, v78
	v_mul_f32_e32 v78, 0xbfb8aa3b, v100
	s_waitcnt lgkmcnt(13)
	v_mfma_f32_16x16x32_bf16 v[182:185], v[194:197], v[92:95], 0
	v_mul_f32_e32 v102, 0xbfb8aa3b, v101
	v_exp_f32_e32 v78, v78
	v_exp_f32_e32 v102, v102
	s_waitcnt lgkmcnt(11)
	v_mfma_f32_16x16x32_bf16 v[186:189], v[238:241], v[92:95], 0
	v_add_f32_e32 v78, 1.0, v78
	v_add_f32_e32 v102, 1.0, v102
	v_rcp_f32_e32 v78, v78
	s_waitcnt lgkmcnt(9)
	v_mfma_f32_16x16x32_bf16 v[92:95], v[246:249], v[92:95], 0
	v_rcp_f32_e32 v102, v102
	v_mul_f32_e32 v100, v78, v100
	v_mul_f32_e32 v101, v102, v101
	v_mfma_f32_16x16x32_bf16 v[178:181], v[190:193], v[88:91], v[178:181]
	v_lshlrev_b32_e32 v108, 16, v79
	v_and_b32_e32 v109, 0xffff0000, v79
	v_mul_f32_e32 v79, 0xbfb8aa3b, v108
	v_mfma_f32_16x16x32_bf16 v[182:185], v[202:205], v[88:91], v[182:185]
	v_mul_f32_e32 v102, 0xbfb8aa3b, v109
	v_exp_f32_e32 v79, v79
	v_exp_f32_e32 v102, v102
	v_mfma_f32_16x16x32_bf16 v[186:189], v[242:245], v[88:91], v[186:189]
	v_add_f32_e32 v79, 1.0, v79
	v_add_f32_e32 v102, 1.0, v102
	v_rcp_f32_e32 v79, v79
	s_waitcnt lgkmcnt(8)
	v_mfma_f32_16x16x32_bf16 v[88:91], v[250:253], v[88:91], v[92:95]
	v_rcp_f32_e32 v102, v102
	v_mul_f32_e32 v108, v79, v108
	v_mul_f32_e32 v109, v102, v109
	s_nop 2
	ds_read_b128 v[92:95], v132
	ds_read_b128 v[190:193], v138
	ds_read_b128 v[194:197], v139
	ds_read_b128 v[202:205], v140
	ds_read_b128 v[238:241], v141
	ds_read_b128 v[242:245], v142
	ds_read_b128 v[246:249], v143
	ds_read_b128 v[250:253], v144
	s_waitcnt lgkmcnt(14)
	v_mfma_f32_16x16x32_bf16 v[178:181], v[206:209], v[84:87], v[178:181]
	v_lshlrev_b32_e32 v110, 16, v72
	v_and_b32_e32 v111, 0xffff0000, v72
	v_mul_f32_e32 v72, 0xbfb8aa3b, v110
	s_waitcnt lgkmcnt(13)
	v_mfma_f32_16x16x32_bf16 v[182:185], v[214:217], v[84:87], v[182:185]
	v_mul_f32_e32 v102, 0xbfb8aa3b, v111
	v_exp_f32_e32 v72, v72
	v_exp_f32_e32 v102, v102
	s_waitcnt lgkmcnt(11)
	v_mfma_f32_16x16x32_bf16 v[186:189], v[222:225], v[84:87], v[186:189]
	v_add_f32_e32 v72, 1.0, v72
	v_add_f32_e32 v102, 1.0, v102
	v_rcp_f32_e32 v72, v72
	s_waitcnt lgkmcnt(9)
	v_mfma_f32_16x16x32_bf16 v[84:87], v[230:233], v[84:87], v[88:91]
	v_rcp_f32_e32 v102, v102
	v_mul_f32_e32 v110, v72, v110
	v_mul_f32_e32 v111, v102, v111
	v_mfma_f32_16x16x32_bf16 v[88:91], v[210:213], v[80:83], v[178:181]
	v_lshlrev_b32_e32 v112, 16, v73
	v_and_b32_e32 v113, 0xffff0000, v73
	v_mul_f32_e32 v73, 0xbfb8aa3b, v112
	v_mfma_f32_16x16x32_bf16 v[178:181], v[218:221], v[80:83], v[182:185]
	v_mul_f32_e32 v102, 0xbfb8aa3b, v113
	v_exp_f32_e32 v73, v73
	v_exp_f32_e32 v102, v102
	s_nop 2
	ds_read_b128 v[182:185], v133
	ds_read_b128 v[206:209], v145
	ds_read_b128 v[210:213], v146
	ds_read_b128 v[214:217], v147
	v_mfma_f32_16x16x32_bf16 v[186:189], v[226:229], v[80:83], v[186:189]
	v_add_f32_e32 v73, 1.0, v73
	v_add_f32_e32 v102, 1.0, v102
	v_rcp_f32_e32 v73, v73
	ds_read_b128 v[218:221], v148
	ds_read_b128 v[222:225], v149
	ds_read_b128 v[226:229], v150
	ds_read_b128 v[230:233], v151
	s_waitcnt lgkmcnt(14)
	v_mfma_f32_16x16x32_bf16 v[80:83], v[234:237], v[80:83], v[84:87]
	v_rcp_f32_e32 v102, v102
	v_mul_f32_e32 v112, v73, v112
	v_mul_f32_e32 v113, v102, v113
	v_mfma_f32_16x16x32_bf16 v[84:87], v[92:95], v[128:131], 0
	v_lshlrev_b32_e32 v114, 16, v74
	v_and_b32_e32 v115, 0xffff0000, v74
	v_mul_f32_e32 v74, 0xbfb8aa3b, v114
	s_waitcnt lgkmcnt(13)
	v_mfma_f32_16x16x32_bf16 v[92:95], v[194:197], v[128:131], 0
	v_mul_f32_e32 v102, 0xbfb8aa3b, v115
	v_exp_f32_e32 v74, v74
	v_exp_f32_e32 v102, v102
	s_waitcnt lgkmcnt(11)
	v_mfma_f32_16x16x32_bf16 v[194:197], v[238:241], v[128:131], 0
	v_add_f32_e32 v74, 1.0, v74
	v_add_f32_e32 v102, 1.0, v102
	v_rcp_f32_e32 v74, v74
	s_waitcnt lgkmcnt(9)
	v_mfma_f32_16x16x32_bf16 v[128:131], v[246:249], v[128:131], 0
	v_rcp_f32_e32 v102, v102
	v_mul_f32_e32 v114, v74, v114
	v_mul_f32_e32 v115, v102, v115
	v_mfma_f32_16x16x32_bf16 v[84:87], v[190:193], v[174:177], v[84:87]
	v_lshlrev_b32_e32 v116, 16, v75
	v_and_b32_e32 v117, 0xffff0000, v75
	v_mul_f32_e32 v75, 0xbfb8aa3b, v116
	v_mfma_f32_16x16x32_bf16 v[92:95], v[202:205], v[174:177], v[92:95]
	v_mul_f32_e32 v102, 0xbfb8aa3b, v117
	v_exp_f32_e32 v75, v75
	v_exp_f32_e32 v102, v102
	v_mfma_f32_16x16x32_bf16 v[190:193], v[242:245], v[174:177], v[194:197]
	v_add_f32_e32 v75, 1.0, v75
	v_add_f32_e32 v102, 1.0, v102
	v_rcp_f32_e32 v75, v75
	s_waitcnt lgkmcnt(8)
	v_mfma_f32_16x16x32_bf16 v[128:131], v[250:253], v[174:177], v[128:131]
	v_rcp_f32_e32 v102, v102
	v_mul_f32_e32 v116, v75, v116
	v_mul_f32_e32 v117, v102, v117
	s_cmp_lg_u64 s[8:9], 0
	s_cbranch_scc0 .Lscan_zpf_skip
	v_lshl_add_u64 v[72:73], s[92:93], 0, v[122:123]
	s_mov_b64 s[10:11], 0x2001000
	v_lshl_add_u64 v[72:73], v[72:73], 0, s[6:7]
	v_lshl_add_u64 v[72:73], v[72:73], 0, s[10:11]
	global_load_dwordx4 v[76:79], v[72:73], off offset:128
	global_load_dwordx4 v[72:75], v[72:73], off offset:144
